# scan: slice U/gt wait moved to loop top + hand-written loader loop (DMA issued at top of step, z waited after the barrier), ops DMA nt as baseline
# speedup vs baseline: 1.0078x; 1.0078x over previous
; __device__ __forceinline__ float bflo(unsigned w) { return __uint_as_float(w << 16); }
; __device__ __forceinline__ float bfhi(unsigned w) { return __uint_as_float(w & 0xffff0000u); }
; __device__ __forceinline__ void scan_chain(const Params& P, bool smp, int s, int h, int sl, int lane) {
;     const int l15 = lane & 15, q4 = lane >> 4, e = 16 * sl + l15;
;     const int cu0 = smp ? 1024 + s : s * 128, nsteps = smp ? 1 : 128;
;     f32x4 S[4];
; #pragma unroll
;     for (int tau = 0; tau < 4; ++tau)
; #pragma unroll
;         for (int r = 0; r < 4; ++r) S[tau][r] = smp ? P.state_gdn[(((size_t)s * 8 + h) * 64 + 16 * tau + 4 * q4 + r) * 64 + e] : 0.f;
;     const float* GT = (const float*)(P.ws + WS_GT);
;     float* OA = (float*)((unsigned char*)P.out + YO_OA); float* OAS = (float*)(P.ws + WS_OAS);
; #pragma unroll 1
;     for (int n = 0; n < nsteps; ++n) {
;         const int cu = cu0 + n; const unsigned char* ops = P.ws + WS_OPS + ((size_t)cu * 8 + h) * OPS_UNIT;
;         const float gt = GT[cu * 8 + h];
;         const bf16x8* Wf = (const bf16x8*)(ops + OPS_W) + lane; const bf16x8* KT = (const bf16x8*)(ops + OPS_KT) + lane;
;         const bf16x8* QD = (const bf16x8*)(ops + OPS_QD) + lane; const bf16x8* QK = (const bf16x8*)(ops + OPS_QK) + lane;
;         const v2u* Up = (const v2u*)(ops + OPS_U) + (sl * 4) * 64 + lane;
;         bf16x8 Sb[2]; Sb[0] = pack8(S[0], S[1]); Sb[1] = pack8(S[2], S[3]);
;         f32x4 vn[4];
; #pragma unroll
;         for (int tau = 0; tau < 4; ++tau) { f32x4 av = {0.f, 0.f, 0.f, 0.f}; av = mfma16(Wf[(2 * tau) * 64], Sb[0], av); av = mfma16(Wf[(2 * tau + 1) * 64], Sb[1], av);
;             const v2u ub = Up[tau * 64]; const f32x4 u = {bflo(ub.x), bfhi(ub.x), bflo(ub.y), bfhi(ub.y)}; vn[tau] = u - av; }
;         bf16x8 Vb[2]; Vb[0] = pack8(vn[0], vn[1]); Vb[1] = pack8(vn[2], vn[3]);
;         f32x4 ao[4];
; #pragma unroll
;         for (int tau = 0; tau < 4; ++tau) { f32x4 a = {0.f, 0.f, 0.f, 0.f}; a = mfma16(QD[(2 * tau) * 64], Sb[0], a); a = mfma16(QD[(2 * tau + 1) * 64], Sb[1], a);
;             a = mfma16(QK[((tau < 2) ? tau : 2 * tau - 2) * 64], Vb[0], a); if (tau >= 2) a = mfma16(QK[(2 * tau - 1) * 64], Vb[1], a); ao[tau] = a; }
; #pragma unroll
;         for (int tau = 0; tau < 4; ++tau) { f32x4 a = S[tau] * gt; a = mfma16(KT[(2 * tau) * 64], Vb[0], a); a = mfma16(KT[(2 * tau + 1) * 64], Vb[1], a); S[tau] = a; }
.LBB0_639:
	v_readlane_b32 s18, v247, 0
	v_readlane_b32 s19, v247, 1
	s_add_u32 s29, s18, 0x1400000
	s_addc_u32 s30, s19, 0
	s_ashr_i32 s8, s96, 3
	s_lshl_b32 s0, s8, 7
	s_ashr_i32 s1, s0, 31
	s_and_b32 s2, s96, 7
	s_lshl_b64 s[14:15], s[0:1], 3
	s_add_u32 s10, s18, 0x3600000
	s_addc_u32 s11, s19, 0
	s_add_u32 s4, s18, 0xb700000
	s_addc_u32 s5, s19, 0
	s_ashr_i32 s9, s8, 31
	s_add_u32 s22, s18, 0x23900000
	s_addc_u32 s23, s19, 0
	s_or_b32 s12, s14, s2
	s_mul_i32 s13, s15, 0xa000
	s_mul_hi_u32 s16, s12, 0xa000
	s_add_i32 s16, s16, s13
	s_mul_i32 s12, s12, 0xa000
	s_add_u32 s12, s22, s12
	s_addc_u32 s13, s23, s16
	s_add_u32 s16, s18, 0x3d300000
	s_addc_u32 s17, s19, 0
	s_lshl_b32 s28, s96, 1
	s_ashr_i32 s18, s40, 8
	s_add_i32 s18, s18, s28
	s_ashr_i32 s26, s18, 3
	s_ashr_i32 s27, s26, 31
	s_and_b32 s34, s18, 7
	v_lshrrev_b32_e32 v1, 4, v164
	s_lshl_b64 s[18:19], s[26:27], 9
	v_and_b32_e32 v30, 15, v35
	v_lshl_or_b32 v2, v1, 2, s18
	s_bfe_u32 s24, s40, 0x20006
	v_lshl_or_b32 v2, s34, 6, v2
	v_mov_b32_e32 v3, s19
	v_lshlrev_b32_e32 v4, 2, v30
	v_mov_b32_e32 v165, 0
	v_lshl_or_b32 v4, s24, 6, v4
	v_mov_b32_e32 v5, v165
	v_lshlrev_b64 v[2:3], 8, v[2:3]
	v_lshl_add_u64 v[14:15], s[74:75], 0, v[4:5]
	v_or_b32_e32 v10, 0x1100, v2
	v_mov_b32_e32 v11, v3
	v_or_b32_e32 v8, 0x1000, v2
	v_mov_b32_e32 v9, v3
	v_lshl_add_u64 v[16:17], v[14:15], 0, v[10:11]
	v_or_b32_e32 v10, 0x1200, v2
	v_lshl_add_u64 v[6:7], v[14:15], 0, v[2:3]
	v_lshl_add_u64 v[8:9], v[14:15], 0, v[8:9]
	v_lshl_add_u64 v[18:19], v[14:15], 0, v[10:11]
	v_or_b32_e32 v10, 0x1300, v2
	s_add_i32 s18, s26, 0x400
	v_lshl_add_u64 v[20:21], v[14:15], 0, v[10:11]
	global_load_dword v10, v[6:7], off
	global_load_dword v11, v[6:7], off offset:256
	global_load_dword v12, v[6:7], off offset:512
	global_load_dword v13, v[6:7], off offset:768
	s_nop 0
	global_load_dword v6, v[8:9], off
	global_load_dword v7, v[16:17], off
	s_nop 0
	global_load_dword v8, v[18:19], off
	global_load_dword v9, v[20:21], off
	v_or_b32_e32 v18, 0x2100, v2
	v_mov_b32_e32 v19, v3
	s_ashr_i32 s19, s18, 31
	v_lshl_add_u64 v[22:23], v[14:15], 0, v[18:19]
	v_or_b32_e32 v18, 0x2200, v2
	s_lshl_b64 s[20:21], s[18:19], 3
	v_lshl_add_u64 v[28:29], v[14:15], 0, v[18:19]
	v_or_b32_e32 v18, 0x2300, v2
	s_or_b32 s19, s20, s34
	v_lshl_add_u64 v[32:33], v[14:15], 0, v[18:19]
	v_or_b32_e32 v18, 0x3000, v2
	s_mul_i32 s20, s21, 0xa000
	s_mul_hi_u32 s21, s19, 0xa000
	v_lshl_add_u64 v[36:37], v[14:15], 0, v[18:19]
	v_or_b32_e32 v18, 0x3100, v2
	s_add_i32 s21, s21, s20
	s_mul_i32 s19, s19, 0xa000
	v_or_b32_e32 v16, 0x2000, v2
	v_mov_b32_e32 v17, v3
	v_lshl_add_u64 v[38:39], v[14:15], 0, v[18:19]
	v_or_b32_e32 v18, 0x3200, v2
	s_add_u32 s20, s22, s19
	v_lshl_add_u64 v[16:17], v[14:15], 0, v[16:17]
	v_lshl_add_u64 v[40:41], v[14:15], 0, v[18:19]
	v_or_b32_e32 v2, 0x3300, v2
	s_addc_u32 s21, s23, s21
	v_lshlrev_b32_e32 v18, 4, v164
	v_lshl_add_u64 v[2:3], v[14:15], 0, v[2:3]
	global_load_dwordx4 v[24:27], v18, s[20:21]
	global_load_dword v20, v[16:17], off
	global_load_dword v21, v[22:23], off
	s_nop 0
	global_load_dword v22, v[28:29], off
	global_load_dword v23, v[32:33], off
	global_load_dword v14, v[36:37], off
	global_load_dword v15, v[38:39], off
	global_load_dword v16, v[40:41], off
	global_load_dword v17, v[2:3], off
	s_lshl_b32 s18, s18, 3
	global_load_dwordx4 v[36:39], v18, s[20:21] offset:1024
	global_load_dwordx4 v[40:43], v18, s[20:21] offset:2048
	s_or_b32 s18, s18, s34
	s_ashr_i32 s19, s18, 31
	s_lshl_b64 s[18:19], s[18:19], 2
	s_add_u32 s18, s29, s18
	s_addc_u32 s19, s30, s19
	s_lshl_b32 s22, s24, 11
	s_add_u32 s22, s20, s22
	s_addc_u32 s23, s21, 0
	v_lshlrev_b32_e32 v2, 3, v164
	v_mov_b32_e32 v3, v165
	v_lshl_add_u64 v[32:33], s[22:23], 0, v[2:3]
	s_mov_b32 s31, 0x8000
	v_mov_b32_e32 v19, v165
	v_add_co_u32_e32 v44, vcc, s31, v32
	s_movk_i32 s36, 0x2000
	v_lshl_add_u64 v[28:29], s[20:21], 0, v[18:19]
	v_addc_co_u32_e32 v45, vcc, 0, v33, vcc
	v_add_co_u32_e32 v82, vcc, s36, v28
	global_load_dwordx2 v[96:97], v[44:45], off
	s_nop 0
	global_load_dwordx4 v[44:47], v18, s[20:21] offset:3072
	v_addc_co_u32_e32 v83, vcc, 0, v29, vcc
	global_load_dwordx4 v[48:51], v[82:83], off offset:-4096
	s_movk_i32 s35, 0x1000
	v_add_co_u32_e32 v60, vcc, s35, v28
	s_mov_b64 s[24:25], 0x8000
	s_nop 0
	v_addc_co_u32_e32 v61, vcc, 0, v29, vcc
	global_load_dwordx4 v[52:55], v[60:61], off offset:1024
	v_lshl_add_u64 v[32:33], v[32:33], 0, s[24:25]
	global_load_dwordx2 v[98:99], v[32:33], off offset:512
	global_load_dwordx4 v[56:59], v[60:61], off offset:2048
	s_nop 0
	global_load_dwordx4 v[60:63], v[60:61], off offset:3072
	s_movk_i32 s22, 0x4000
	s_mov_b64 s[20:21], 0x4000
	v_add_co_u32_e32 v64, vcc, s22, v28
	v_lshl_add_u64 v[68:69], v[28:29], 0, s[20:21]
	s_nop 0
	v_addc_co_u32_e32 v65, vcc, 0, v29, vcc
	s_movk_i32 s20, 0x6000
	v_add_co_u32_e32 v72, vcc, s20, v28
	global_load_dwordx4 v[64:67], v[64:65], off
	s_nop 0
	v_addc_co_u32_e32 v73, vcc, 0, v29, vcc
	global_load_dwordx4 v[68:71], v[68:69], off offset:1024
	s_nop 0
	global_load_dwordx4 v[72:75], v[72:73], off
	s_nop 0
	global_load_dwordx2 v[100:101], v[32:33], off offset:1024
	s_nop 0
	global_load_dwordx2 v[32:33], v[32:33], off offset:1536
	s_nop 0
	global_load_dword v34, v165, s[18:19]
	s_waitcnt vmcnt(30)
	v_cvt_pk_bf16_f32 v76, v10, v11
	s_waitcnt vmcnt(28)
	v_cvt_pk_bf16_f32 v77, v12, v13
	s_waitcnt vmcnt(26)
	v_cvt_pk_bf16_f32 v78, v6, v7
	s_waitcnt vmcnt(24)
	v_cvt_pk_bf16_f32 v79, v8, v9
	s_mov_b64 s[18:19], 0x2000
	v_lshl_add_u64 v[92:93], v[28:29], 0, s[18:19]
	s_waitcnt vmcnt(23)
	v_mfma_f32_16x16x32_bf16 v[24:27], v[24:27], v[76:79], 0
	global_load_dwordx4 v[84:87], v[82:83], off
	global_load_dwordx4 v[88:91], v[92:93], off offset:1024
	s_waitcnt vmcnt(23)
; __device__ __forceinline__ float bflo(unsigned w) { return __uint_as_float(w << 16); }
; __device__ __forceinline__ float bfhi(unsigned w) { return __uint_as_float(w & 0xffff0000u); }
; __device__ __forceinline__ f32x4 mfma16(bf16x8 a, bf16x8 b, f32x4 c) { return __builtin_amdgcn_mfma_f32_16x16x32_bf16(a, b, c, 0, 0, 0); }
; __device__ __forceinline__ bf16x8 pack8(f32x4 a, f32x4 b) { v4u w; w.x = pk2(a[0], a[1]); w.y = pk2(a[2], a[3]); w.z = pk2(b[0], b[1]); w.w = pk2(b[2], b[3]); return __builtin_bit_cast(bf16x8, w); }
; __device__ __forceinline__ void scan_chain(const Params& P, bool smp, int s, int h, int sl, int lane) {
;     ...
;         bf16x8 Sb[2]; Sb[0] = pack8(S[0], S[1]); Sb[1] = pack8(S[2], S[3]);
;         f32x4 vn[4];
; #pragma unroll
;         for (int tau = 0; tau < 4; ++tau) { f32x4 av = {0.f, 0.f, 0.f, 0.f}; av = mfma16(Wf[(2 * tau) * 64], Sb[0], av); av = mfma16(Wf[(2 * tau + 1) * 64], Sb[1], av);
;             const v2u ub = Up[tau * 64]; const f32x4 u = {bflo(ub.x), bfhi(ub.x), bflo(ub.y), bfhi(ub.y)}; vn[tau] = u - av; }
;         bf16x8 Vb[2]; Vb[0] = pack8(vn[0], vn[1]); Vb[1] = pack8(vn[2], vn[3]);
;         f32x4 ao[4];
; #pragma unroll
;         for (int tau = 0; tau < 4; ++tau) { f32x4 a = {0.f, 0.f, 0.f, 0.f}; a = mfma16(QD[(2 * tau) * 64], Sb[0], a); a = mfma16(QD[(2 * tau + 1) * 64], Sb[1], a);
;             a = mfma16(QK[((tau < 2) ? tau : 2 * tau - 2) * 64], Vb[0], a); if (tau >= 2) a = mfma16(QK[(2 * tau - 1) * 64], Vb[1], a); ao[tau] = a; }
; #pragma unroll
;         for (int tau = 0; tau < 4; ++tau) { f32x4 a = S[tau] * gt; a = mfma16(KT[(2 * tau) * 64], Vb[0], a); a = mfma16(KT[(2 * tau + 1) * 64], Vb[1], a); S[tau] = a; }
;         if (!smp) { float* op = OA + ((size_t)s * TP + n * 64) * 512 + h * 64 + e;
; #pragma unroll
;             for (int tau = 0; tau < 4; ++tau)
; #pragma unroll
;                 for (int r = 0; r < 4; ++r) op[(size_t)(16 * tau + 4 * q4 + r) * 512] = ao[tau][r];
;         } else { float* op = OAS + ((size_t)s * 16) * 512 + h * 64 + e;
; #pragma unroll
;             for (int r = 0; r < 4; ++r) op[(size_t)(4 * q4 + r) * 512] = ao[0][r]; }
;     }
;     float* so = P.out + (smp ? O_GS : O_GP) + (((size_t)s * 8 + h) * 64) * 64 + e;
; #pragma unroll
;     for (int tau = 0; tau < 4; ++tau)
; #pragma unroll
;         for (int r = 0; r < 4; ++r) so[(size_t)(16 * tau + 4 * q4 + r) * 64] = S[tau][r];
	v_cvt_pk_bf16_f32 v80, v20, v21
	s_waitcnt vmcnt(21)
	v_cvt_pk_bf16_f32 v81, v22, v23
	s_waitcnt vmcnt(15)
	v_mfma_f32_16x16x32_bf16 v[40:43], v[40:43], v[76:79], 0
	v_cvt_pk_bf16_f32 v82, v14, v15
	v_cvt_pk_bf16_f32 v83, v16, v17
	s_movk_i32 s18, 0x3000
	v_readlane_b32 s72, v247, 7
	v_mfma_f32_16x16x32_bf16 v[24:27], v[36:39], v[80:83], v[24:27]
	global_load_dwordx4 v[36:39], v[92:93], off offset:2048
	v_readlane_b32 s82, v247, 17
	global_load_dwordx4 v[92:95], v[92:93], off offset:3072
	s_waitcnt vmcnt(15)
	v_mfma_f32_16x16x32_bf16 v[40:43], v[44:47], v[80:83], v[40:43]
	v_lshlrev_b32_e32 v19, 16, v96
	v_and_b32_e32 v31, 0xffff0000, v96
	s_nop 0
	v_sub_f32_e32 v31, v31, v25
	s_waitcnt vmcnt(14)
	v_mfma_f32_16x16x32_bf16 v[44:47], v[48:51], v[76:79], 0
	v_lshlrev_b32_e32 v48, 16, v97
	v_and_b32_e32 v49, 0xffff0000, v97
	v_sub_f32_e32 v96, v49, v27
	s_waitcnt vmcnt(13)
	v_mfma_f32_16x16x32_bf16 v[44:47], v[52:55], v[80:83], v[44:47]
	v_sub_f32_e32 v52, v48, v26
	v_sub_f32_e32 v19, v19, v24
	s_waitcnt vmcnt(12)
	v_lshlrev_b32_e32 v53, 16, v98
	s_waitcnt vmcnt(11)
	v_mfma_f32_16x16x32_bf16 v[24:27], v[56:59], v[76:79], 0
	v_and_b32_e32 v54, 0xffff0000, v98
	v_lshlrev_b32_e32 v48, 16, v99
	v_sub_f32_e32 v53, v53, v40
	s_waitcnt vmcnt(10)
	v_mfma_f32_16x16x32_bf16 v[24:27], v[60:63], v[80:83], v[24:27]
	v_cvt_pk_bf16_f32 v40, v19, v31
	v_sub_f32_e32 v55, v48, v42
	s_waitcnt vmcnt(6)
	v_lshlrev_b32_e32 v19, 16, v100
	v_and_b32_e32 v31, 0xffff0000, v100
	v_sub_f32_e32 v42, v54, v41
	v_sub_f32_e32 v31, v31, v45
	v_sub_f32_e32 v19, v19, v44
	v_cvt_pk_bf16_f32 v41, v52, v96
	v_cvt_pk_bf16_f32 v42, v53, v42
	v_lshlrev_b32_e32 v52, 16, v101
	v_and_b32_e32 v53, 0xffff0000, v101
	v_cvt_pk_bf16_f32 v44, v19, v31
	s_waitcnt vmcnt(5)
	v_lshlrev_b32_e32 v19, 16, v32
	v_and_b32_e32 v31, 0xffff0000, v32
	v_lshlrev_b32_e32 v32, 16, v33
	v_sub_f32_e32 v47, v53, v47
	v_sub_f32_e32 v46, v52, v46
	v_and_b32_e32 v33, 0xffff0000, v33
	v_sub_f32_e32 v52, v32, v26
	v_add_co_u32_e32 v32, vcc, s18, v28
	v_cvt_pk_bf16_f32 v45, v46, v47
	v_sub_f32_e32 v47, v33, v27
	v_addc_co_u32_e32 v33, vcc, 0, v29, vcc
	global_load_dwordx4 v[26:29], v[32:33], off offset:3072
	global_load_dwordx4 v[56:59], v[32:33], off offset:2048
	v_and_b32_e32 v49, 0xffff0000, v99
	v_sub_f32_e32 v43, v49, v43
	v_cvt_pk_bf16_f32 v43, v55, v43
	v_cvt_pk_bf16_f32 v47, v52, v47
	global_load_dwordx4 v[52:55], v[32:33], off
	s_waitcnt vmcnt(7)
	v_pk_mul_f32 v[8:9], v[8:9], v[34:35] op_sel_hi:[1,0]
	v_pk_mul_f32 v[6:7], v[6:7], v[34:35] op_sel_hi:[1,0]
	v_mfma_f32_16x16x32_bf16 v[48:51], v[64:67], v[76:79], 0
	s_lshl_b64 s[18:19], s[26:27], 15
	s_add_u32 s18, s16, s18
	v_pk_mul_f32 v[16:17], v[16:17], v[34:35] op_sel_hi:[1,0]
	s_waitcnt vmcnt(4)
	v_mfma_f32_16x16x32_bf16 v[6:9], v[36:39], v[40:43], v[6:9]
	global_load_dwordx4 v[36:39], v[32:33], off offset:1024
	v_pk_mul_f32 v[14:15], v[14:15], v[34:35] op_sel_hi:[1,0]
	s_addc_u32 s19, s17, s19
	v_mfma_f32_16x16x32_bf16 v[48:51], v[68:71], v[80:83], v[48:51]
	s_lshl_b32 s20, s34, 8
	s_add_u32 s18, s18, s20
	v_sub_f32_e32 v25, v31, v25
	s_waitcnt vmcnt(2)
	v_mfma_f32_16x16x32_bf16 v[14:17], v[56:59], v[40:43], v[14:17]
	v_sub_f32_e32 v19, v19, v24
	s_addc_u32 s19, s19, 0
	v_cvt_pk_bf16_f32 v46, v19, v25
	v_mfma_f32_16x16x32_bf16 v[48:51], v[72:75], v[40:43], v[48:51]
	v_lshl_add_u64 v[24:25], s[18:19], 0, v[4:5]
	s_lshl_b64 s[18:19], s[26:27], 17
	v_pk_mul_f32 v[12:13], v[12:13], v[34:35] op_sel_hi:[1,0]
	v_pk_mul_f32 v[10:11], v[10:11], v[34:35] op_sel_hi:[1,0]
	v_mfma_f32_16x16x32_bf16 v[14:17], v[26:29], v[44:47], v[14:17]
	v_lshlrev_b32_e32 v26, 13, v1
	v_mov_b32_e32 v27, v165
	s_add_u32 s18, s54, s18
	v_mfma_f32_16x16x32_bf16 v[10:13], v[84:87], v[40:43], v[10:13]
	v_lshl_add_u64 v[24:25], v[24:25], 0, v[26:27]
	s_addc_u32 s19, s55, s19
	s_lshl_b32 s20, s34, 14
	global_store_dword v[24:25], v48, off
	global_store_dword v[24:25], v49, off offset:2048
	v_add_co_u32_e32 v24, vcc, s35, v24
	s_add_u32 s18, s18, s20
	s_nop 0
	v_addc_co_u32_e32 v25, vcc, 0, v25, vcc
	s_addc_u32 s19, s19, 0
	v_pk_mul_f32 v[22:23], v[22:23], v[34:35] op_sel_hi:[1,0]
	v_pk_mul_f32 v[20:21], v[20:21], v[34:35] op_sel_hi:[1,0]
	global_store_dword v[24:25], v50, off
	global_store_dword v[24:25], v51, off offset:2048
	v_lshl_add_u64 v[4:5], s[18:19], 0, v[4:5]
	v_lshlrev_b32_e32 v24, 10, v1
	v_mov_b32_e32 v25, v165
	v_mfma_f32_16x16x32_bf16 v[10:13], v[88:91], v[44:47], v[10:13]
	v_lshl_add_u64 v[4:5], v[4:5], 0, v[24:25]
	s_mov_b64 s[18:19], 0x1126c000
	v_lshl_add_u64 v[24:25], v[4:5], 0, s[18:19]
	s_waitcnt vmcnt(5)
	v_mfma_f32_16x16x32_bf16 v[20:23], v[52:55], v[40:43], v[20:23]
	s_mov_b32 s18, 0x1126d000
	v_add_co_u32_e32 v26, vcc, s18, v4
	v_mfma_f32_16x16x32_bf16 v[6:9], v[92:95], v[44:47], v[6:9]
	s_nop 0
	v_addc_co_u32_e32 v27, vcc, 0, v5, vcc
	s_mov_b32 s18, 0x1126e000
	s_waitcnt vmcnt(4)
	v_mfma_f32_16x16x32_bf16 v[20:23], v[36:39], v[44:47], v[20:23]
	global_store_dword v[26:27], v10, off offset:-4096
	global_store_dword v[24:25], v11, off offset:256
	global_store_dword v[24:25], v12, off offset:512
	global_store_dword v[24:25], v13, off offset:768
	global_store_dword v[26:27], v6, off
	global_store_dword v[26:27], v7, off offset:256
	global_store_dword v[26:27], v8, off offset:512
	global_store_dword v[26:27], v9, off offset:768
	v_add_co_u32_e32 v6, vcc, s18, v4
	s_mov_b32 s18, 0x1126f000
	s_nop 0
	v_addc_co_u32_e32 v7, vcc, 0, v5, vcc
	v_add_co_u32_e32 v4, vcc, s18, v4
	v_ashrrev_i32_e32 v1, 8, v35
	s_nop 0
	v_addc_co_u32_e32 v5, vcc, 0, v5, vcc
	v_add_u32_e32 v1, s28, v1
	global_store_dword v[4:5], v20, off offset:-4096
	global_store_dword v[6:7], v21, off offset:256
	global_store_dword v[6:7], v22, off offset:512
	global_store_dword v[6:7], v23, off offset:768
	global_store_dword v[4:5], v14, off
	global_store_dword v[4:5], v15, off offset:256
	global_store_dword v[4:5], v16, off offset:512
	global_store_dword v[4:5], v17, off offset:768
	v_ashrrev_i32_e32 v4, 3, v1
	v_ashrrev_i32_e32 v5, 31, v4
	v_lshrrev_b32_e32 v6, 4, v35
	v_lshlrev_b64 v[8:9], 4, v[4:5]
	v_and_or_b32 v8, v6, 15, v8
	v_lshlrev_b32_e32 v1, 6, v1
	v_lshlrev_b64 v[4:5], 11, v[8:9]
	v_and_b32_e32 v1, 0x1c0, v1
	v_lshl_add_u64 v[4:5], s[16:17], 0, v[4:5]
	v_lshlrev_b32_e32 v6, 2, v1
	v_mov_b32_e32 v7, v165
	v_lshl_add_u64 v[4:5], v[4:5], 0, v[6:7]
	v_lshlrev_b32_e32 v6, 2, v35
	v_and_b32_e32 v12, 60, v6
	v_lshlrev_b32_e32 v10, 2, v12
	v_mov_b32_e32 v11, v165
	v_lshl_add_u64 v[4:5], v[4:5], 0, v[10:11]
	s_waitcnt vmcnt(0)
	s_barrier
; __device__ __forceinline__ unsigned pk2(float lo, float hi) { return pg8::cvt_pk_bf16_v(lo, hi); }
; __device__ __forceinline__ float bflo(unsigned w) { return __uint_as_float(w << 16); }
; __device__ __forceinline__ float bfhi(unsigned w) { return __uint_as_float(w & 0xffff0000u); }
; __device__ __forceinline__ void scan_prompt_wg(const Params& P, LAS unsigned char* lds, int s, int h, int wave, int lane) {
;     ...
;         const int sl = wave, l15 = lane & 15, q4 = lane >> 4, e = 16 * sl + l15;
;         f32x4 S[4];
; #pragma unroll
;         for (int tau = 0; tau < 4; ++tau) S[tau] = (f32x4){0.f, 0.f, 0.f, 0.f};
;         const float* GT = (const float*)(P.ws + WS_GT) + (size_t)(s * 128) * 8 + h;
;         const v2u* Ug = (const v2u*)(ops0 + OPS_U) + (sl * 4) * 64 + lane;
;         v2u ua[4], ub[4];
; #pragma unroll
;         for (int tau = 0; tau < 4; ++tau) { ua[tau] = Ug[tau * 64]; ub[tau] = (Ug + step_stride / 8)[tau * 64]; }
;         SCAN_BAR();
;         int slot = 0;
;         float gt = GT[0];
; __global__ void __launch_bounds__(NWAVES * 64, 2) fwd_kernel(Params P) {
;     ...
;                 const int pr = (int)blockIdx.x * 2 + (tid >> 8), sp = pr >> 3, hp_ = pr & 7, t = (tid >> 4) & 15, part = tid & 15;
;                 const size_t row = (size_t)sp * 16 + t;
;                 const f32x4 o4 = *(const f32x4*)((const float*)(ws + WS_OAS) + row * 512 + hp_ * 64 + 4 * part);
;                 float ss = (o4[0] * o4[0] + o4[1] * o4[1]) + (o4[2] * o4[2] + o4[3] * o4[3]);
;                 ss += __shfl_xor(ss, 1); ss += __shfl_xor(ss, 2); ss += __shfl_xor(ss, 4); ss += __shfl_xor(ss, 8);
;                 const float rstd = __builtin_amdgcn_rsqf(ss * (1.0f / 64.0f) + 1e-6f);
;                 const size_t mo = ((size_t)MP + row) * 1024 + hp_ * 64 + 4 * part;
;                 const v2u zb = *(const v2u*)((const bf16*)(ws + WS_Z) + mo);
;                 const f32x4 g4 = *(const f32x4*)(P.gdn_g + 4 * part);
;                 v2u o; o.x = pk2(o4[0] * rstd * g4[0] * siluf(bflo(zb.x)), o4[1] * rstd * g4[1] * siluf(bfhi(zb.x))); o.y = pk2(o4[2] * rstd * g4[2] * siluf(bflo(zb.y)), o4[3] * rstd * g4[3] * siluf(bfhi(zb.y)));
;                 *(v2u*)((bf16*)(ws + WS_MIX) + mo) = o;
;             }
;             __syncthreads();
;             REP(30) { scan_prompt_wg(P, lds, (int)blockIdx.x >> 3, (int)blockIdx.x & 7, wave, lane); __syncthreads(); }
	global_load_dwordx4 v[4:7], v[4:5], off
	v_lshlrev_b64 v[8:9], 10, v[8:9]
	v_or3_b32 v8, v8, v1, v12
	v_mov_b64_e32 v[12:13], 0x8000000
	v_lshl_add_u64 v[12:13], v[8:9], 1, v[12:13]
	v_lshl_add_u64 v[8:9], s[10:11], 0, v[12:13]
	global_load_dwordx2 v[14:15], v[8:9], off
	v_readlane_b32 s83, v247, 18
	v_mbcnt_lo_u32_b32 v1, -1, 0
	v_mbcnt_hi_u32_b32 v1, -1, v1
	v_xor_b32_e32 v53, 1, v1
	v_xor_b32_e32 v54, 2, v1
	v_xor_b32_e32 v55, 4, v1
	global_load_dwordx4 v[8:11], v10, s[82:83]
	v_xor_b32_e32 v56, 8, v1
	v_mov_b32_e32 v19, 0x358637bd
	s_mov_b64 s[46:47], s[82:83]
	s_mov_b64 s[16:17], -1
	s_cmp_lt_i32 s33, 4
	s_mul_hi_i32 s26, s0, 0x50000
	s_mul_i32 s27, s0, 0x50000
	s_mul_i32 s28, s2, 0xa000
	v_readlane_b32 s73, v247, 8
	v_readlane_b32 s74, v247, 9
	v_readlane_b32 s75, v247, 10
	v_readlane_b32 s76, v247, 11
	v_readlane_b32 s77, v247, 12
	v_readlane_b32 s78, v247, 13
	v_readlane_b32 s79, v247, 14
	v_readlane_b32 s80, v247, 15
	v_readlane_b32 s81, v247, 16
	v_readlane_b32 s84, v247, 19
	v_readlane_b32 s85, v247, 20
	v_readlane_b32 s86, v247, 21
	v_readlane_b32 s87, v247, 22
	s_waitcnt vmcnt(2)
	v_pk_mul_f32 v[16:17], v[6:7], v[6:7]
	v_pk_mul_f32 v[20:21], v[4:5], v[4:5]
	s_nop 0
	v_pk_mov_b32 v[22:23], v[20:21], v[16:17] op_sel:[1,0]
	v_mov_b32_e32 v21, v17
	v_pk_add_f32 v[16:17], v[22:23], v[20:21]
	s_nop 0
	v_add_f32_e32 v16, v16, v17
	v_and_b32_e32 v17, 64, v1
	v_add_u32_e32 v52, 64, v17
	v_cmp_lt_i32_e32 vcc, v53, v52
	s_nop 1
	v_cndmask_b32_e32 v17, v1, v53, vcc
	v_lshlrev_b32_e32 v57, 2, v17
	ds_bpermute_b32 v17, v57, v16
	v_cmp_lt_i32_e32 vcc, v54, v52
	s_waitcnt lgkmcnt(0)
	v_add_f32_e32 v16, v16, v17
	v_cndmask_b32_e32 v17, v1, v54, vcc
	v_lshlrev_b32_e32 v58, 2, v17
	ds_bpermute_b32 v17, v58, v16
	v_cmp_lt_i32_e32 vcc, v55, v52
	s_waitcnt lgkmcnt(0)
	v_add_f32_e32 v16, v16, v17
	v_cndmask_b32_e32 v17, v1, v55, vcc
	v_lshlrev_b32_e32 v17, 2, v17
	ds_bpermute_b32 v17, v17, v16
	v_cmp_lt_i32_e32 vcc, v56, v52
	s_waitcnt lgkmcnt(0)
	v_add_f32_e32 v16, v16, v17
	v_cndmask_b32_e32 v17, v1, v56, vcc
	v_lshlrev_b32_e32 v17, 2, v17
	ds_bpermute_b32 v17, v17, v16
	s_waitcnt lgkmcnt(0)
	v_add_f32_e32 v16, v16, v17
	v_fmac_f32_e32 v19, 0x3c800000, v16
	s_waitcnt vmcnt(1)
	v_lshlrev_b32_e32 v16, 16, v14
	v_and_b32_e32 v17, 0xffff0000, v14
	v_mul_f32_e32 v14, 0xbfb8aa3b, v16
	v_exp_f32_e32 v20, v14
	v_mul_f32_e32 v14, 0xbfb8aa3b, v17
	v_exp_f32_e32 v21, v14
	v_rsq_f32_e32 v14, v19
	v_add_f32_e32 v19, 1.0, v20
	v_rcp_f32_e32 v20, v19
	v_add_f32_e32 v19, 1.0, v21
	v_rcp_f32_e32 v21, v19
	v_pk_mul_f32 v[4:5], v[4:5], v[14:15] op_sel_hi:[1,0]
	s_waitcnt vmcnt(0)
	v_pk_mul_f32 v[4:5], v[8:9], v[4:5]
	v_pk_mul_f32 v[8:9], v[20:21], v[16:17]
	v_lshlrev_b32_e32 v16, 16, v15
	v_and_b32_e32 v17, 0xffff0000, v15
	v_mul_f32_e32 v15, 0xbfb8aa3b, v16
	v_mul_f32_e32 v19, 0xbfb8aa3b, v17
	v_exp_f32_e32 v15, v15
	v_exp_f32_e32 v19, v19
	v_pk_mul_f32 v[4:5], v[4:5], v[8:9]
	v_add_f32_e32 v8, 1.0, v15
	v_add_f32_e32 v9, 1.0, v19
	v_rcp_f32_e32 v8, v8
	v_rcp_f32_e32 v9, v9
	v_pk_mul_f32 v[6:7], v[6:7], v[14:15] op_sel_hi:[1,0]
	v_cvt_pk_bf16_f32 v4, v4, v5
	v_pk_mul_f32 v[6:7], v[10:11], v[6:7]
	v_pk_mul_f32 v[8:9], v[8:9], v[16:17]
	s_nop 0
	v_pk_mul_f32 v[6:7], v[6:7], v[8:9]
	s_nop 0
	v_cvt_pk_bf16_f32 v5, v6, v7
	v_lshl_add_u64 v[6:7], s[4:5], 0, v[12:13]
	global_store_dwordx2 v[6:7], v[4:5], off
	s_barrier
	s_cbranch_scc0 .LBB0_654
	s_lshl_b32 s16, s33, 8
	s_ashr_i32 s17, s16, 31
	s_lshl_b64 s[16:17], s[16:17], 3
	s_add_u32 s18, s12, s16
	s_addc_u32 s19, s13, s17
	v_lshl_add_u64 v[4:5], s[18:19], 0, v[2:3]
	v_add_co_u32_e32 v8, vcc, s31, v4
	s_mov_b32 s19, 0x58000
	s_nop 0
	v_addc_co_u32_e32 v9, vcc, 0, v5, vcc
	v_lshl_add_u64 v[6:7], v[4:5], 0, s[24:25]
	v_add_co_u32_e32 v4, vcc, s19, v4
	s_lshl_b64 s[14:15], s[14:15], 2
	s_nop 0
	v_addc_co_u32_e32 v5, vcc, 0, v5, vcc
	global_load_dwordx2 v[50:51], v[8:9], off nt
	global_load_dwordx2 v[48:49], v[6:7], off offset:512 nt
	global_load_dwordx2 v[46:47], v[6:7], off offset:1024 nt
	global_load_dwordx2 v[44:45], v[6:7], off offset:1536 nt
	global_load_dwordx2 v[22:23], v[4:5], off nt
	global_load_dwordx2 v[24:25], v[4:5], off offset:512 nt
	global_load_dwordx2 v[26:27], v[4:5], off offset:1024 nt
	global_load_dwordx2 v[28:29], v[4:5], off offset:1536 nt
	s_add_u32 s14, s29, s14
	s_addc_u32 s15, s30, s15
	s_lshl_b32 s18, s2, 2
	s_barrier
	v_mov_b32_e32 v4, s18
	global_load_dword v91, v4, s[14:15]
	s_lshl_b64 s[0:1], s[0:1], 5
	s_or_b32 s0, s0, s18
	v_readlane_b32 s18, v247, 0
	v_readlane_b32 s19, v247, 1
	s_add_u32 s0, s18, s0
	s_addc_u32 s1, s19, s1
	s_add_u32 s14, s0, 0x1400020
	s_addc_u32 s15, s1, 0
	s_add_u32 s0, s27, s28
	s_addc_u32 s1, s26, 0
	s_add_u32 s0, s0, s16
	s_addc_u32 s1, s1, s17
	v_lshrrev_b32_e32 v4, 2, v164
	s_add_u32 s0, s18, s0
	v_and_b32_e32 v73, 12, v4
	s_addc_u32 s1, s19, s1
	v_lshl_or_b32 v20, s33, 4, v30
	v_or_b32_e32 v72, 1, v73
	v_or_b32_e32 v71, 2, v73
	v_or_b32_e32 v70, 3, v4
	v_or_b32_e32 v69, 16, v73
	v_or_b32_e32 v68, 17, v73
	v_or_b32_e32 v67, 18, v73
	v_or_b32_e32 v66, 19, v4
	v_or_b32_e32 v65, 32, v73
	v_or_b32_e32 v64, 33, v73
	v_or_b32_e32 v63, 34, v73
	v_or_b32_e32 v62, 35, v4
	v_or_b32_e32 v61, 48, v73
	v_or_b32_e32 v60, 49, v73
	v_or_b32_e32 v59, 50, v73
	v_or_b32_e32 v19, 51, v4
	v_lshl_add_u64 v[2:3], s[0:1], 0, v[2:3]
	s_mov_b64 s[0:1], 0x239a8400
	s_mov_b32 s31, 0
	v_lshl_add_u32 v21, v20, 1, 0
	v_lshlrev_b32_e32 v74, 7, v73
	v_lshlrev_b32_e32 v75, 7, v72
	v_lshlrev_b32_e32 v76, 7, v71
	v_lshlrev_b32_e32 v77, 7, v70
	v_lshlrev_b32_e32 v78, 7, v69
	v_lshlrev_b32_e32 v79, 7, v68
	v_lshlrev_b32_e32 v80, 7, v67
	v_lshlrev_b32_e32 v81, 7, v66
	v_lshlrev_b32_e32 v82, 7, v65
	v_lshlrev_b32_e32 v83, 7, v64
	v_lshlrev_b32_e32 v84, 7, v63
	v_lshlrev_b32_e32 v85, 7, v62
	v_lshlrev_b32_e32 v86, 7, v61
	v_lshlrev_b32_e32 v87, 7, v60
	v_lshlrev_b32_e32 v88, 7, v59
	v_lshlrev_b32_e32 v89, 7, v19
	v_lshl_add_u32 v90, v164, 4, 0
	v_lshl_add_u64 v[30:31], v[2:3], 0, s[0:1]
	s_mov_b32 s29, 0x1e000
	s_mov_b64 s[16:17], 0x50000
	v_mov_b32_e32 v32, 0
	s_mov_b32 s30, 0
	v_mov_b32_e32 v14, v165
	v_mov_b32_e32 v15, v165
	v_mov_b32_e32 v16, v165
	v_mov_b32_e32 v17, v165
	v_mov_b32_e32 v10, v165
	v_mov_b32_e32 v11, v165
	v_mov_b32_e32 v12, v165
	v_mov_b32_e32 v13, v165
	v_mov_b32_e32 v2, v165
	v_mov_b32_e32 v3, v165
	v_mov_b32_e32 v4, v165
	v_mov_b32_e32 v5, v165
	v_mov_b32_e32 v6, v165
	v_mov_b32_e32 v7, v165
	v_mov_b32_e32 v8, v165
	v_mov_b32_e32 v9, v165
	s_branch .LBB0_643

; #define SCAN_BAR() do { asm volatile("" ::: "memory"); __builtin_amdgcn_s_barrier(); asm volatile("" ::: "memory"); } while (0)
; #define SCAN_ISSUE(n, slot) do { const unsigned char* s_ = src + (size_t)(n) * step_stride; LAS unsigned char* d_ = lds + (slot) * SR_SLOT + p0 * 1024; \
;         _Pragma("unroll") for (int i_ = 0; i_ < 7; ++i_) glds16_asm(s_ + i_ * 1024, d_ + i_ * 1024, true  ); \
;         if (lw < 2) glds16_asm(s_ + 7 * 1024, d_ + 7 * 1024, true); } while (0)
; #define SCAN_ZISSUE(n) do { const unsigned char* z_ = zsrc + (size_t)(n) * 64 * 2048; LAS unsigned char* d_ = lds + ZT_OFF + ((n) & 1) * 8192 + (2 * lw) * 1024; \
;         glds16_asm(z_, d_, false); glds16_asm(z_ + 8 * 2048, d_ + 1024, false); } while (0)
; __device__ __forceinline__ void scan_prompt_wg(const Params& P, LAS unsigned char* lds, int s, int h, int wave, int lane) {
;     ...
;         for (int n = 0; n <= NST; ++n) {
;             if (n >= 1) {
;     ...
;                 asm volatile("s_waitcnt lgkmcnt(0)" ::: "memory");
;                 if (n + 1 < NST) SCAN_ZISSUE(n + 1);
;                 if (n + 3 < NST) SCAN_ISSUE(n + 3, slot);
;                 if (n >= 2 && n + 3 < NST) { if (lw < 2) asm volatile("s_waitcnt vmcnt(20)" ::: "memory"); else asm volatile("s_waitcnt vmcnt(18)" ::: "memory"); }
;                 else asm volatile("s_waitcnt vmcnt(0)" ::: "memory");
;                 slot = (slot == SR_NS - 1) ? 0 : slot + 1;
;                 SCAN_BAR();
.LBB0_666:
	s_add_i32 s45, s10, 1
	s_cmp_eq_u32 s45, 0
	s_cbranch_scc1 .Lld_issue
	s_cmpk_gt_u32 s45, 0x7d
	s_cbranch_scc1 .Lld_zw0
	s_and_b64 vcc, exec, s[8:9]
	s_cbranch_vccnz .Lld_zw18
	s_waitcnt vmcnt(20)
	s_branch .Lld_zwd
.Lld_zw18:
	s_waitcnt vmcnt(18)
	s_branch .Lld_zwd

; #define LAS __attribute__((address_space(3)))
; __device__ __forceinline__ void unpack8(v4u w, float (&f)[8]) { f[0] = bflo(w.x); f[1] = bfhi(w.x); f[2] = bflo(w.y); f[3] = bfhi(w.y); f[4] = bflo(w.z); f[5] = bfhi(w.z); f[6] = bflo(w.w); f[7] = bfhi(w.w); }
; #define SCAN_ISSUE(n, slot) do { const unsigned char* s_ = src + (size_t)(n) * step_stride; LAS unsigned char* d_ = lds + (slot) * SR_SLOT + p0 * 1024; \
;         _Pragma("unroll") for (int i_ = 0; i_ < 7; ++i_) glds16_asm(s_ + i_ * 1024, d_ + i_ * 1024, true  ); \
;         if (lw < 2) glds16_asm(s_ + 7 * 1024, d_ + 7 * 1024, true); } while (0)
; #define SCAN_ZISSUE(n) do { const unsigned char* z_ = zsrc + (size_t)(n) * 64 * 2048; LAS unsigned char* d_ = lds + ZT_OFF + ((n) & 1) * 8192 + (2 * lw) * 1024; \
;         glds16_asm(z_, d_, false); glds16_asm(z_ + 8 * 2048, d_ + 1024, false); } while (0)
; __device__ __forceinline__ void scan_prompt_wg(const Params& P, LAS unsigned char* lds, int s, int h, int wave, int lane) {
;     ...
;         const int ftid = lw * 64 + lane, ft = ftid >> 2, fp = ftid & 3;
;         float gg[16];
; #pragma unroll
;         for (int i = 0; i < 16; ++i) gg[i] = P.gdn_g[16 * fp + i];
;         bf16* Mr = (bf16*)(P.ws + WS_MIX) + ((size_t)s * TP + ft) * 1024 + h * 64 + 16 * fp;
;         const unsigned char* zsrc = (const unsigned char*)((const bf16*)(P.ws + WS_Z) + ((size_t)s * TP + 16 * lw + (lane >> 3)) * 1024 + h * 64) + (lane & 7) * 16;
;     ...
;                 const LAS unsigned char* ot = lds + (((n - 1) & 1) ? OT_B : OT_A) + ft * 128 + fp * 32;
;                 const LAS unsigned char* zt = lds + ZT_OFF + ((n - 1) & 1) * 8192 + ft * 128 + fp * 32;
;                 float o[16], zf[16]; { float t0[8], t1[8]; unpack8(*(const LAS v4u*)ot, t0); unpack8(*(const LAS v4u*)(ot + 16), t1);
; #pragma unroll
;                     for (int i = 0; i < 8; ++i) { o[i] = t0[i]; o[8 + i] = t1[i]; }
;                     unpack8(*(const LAS v4u*)zt, t0); unpack8(*(const LAS v4u*)(zt + 16), t1);
; #pragma unroll
;                     for (int i = 0; i < 8; ++i) { zf[i] = t0[i]; zf[8 + i] = t1[i]; } }
;     ...
;                 asm volatile("s_waitcnt lgkmcnt(0)" ::: "memory");
;                 if (n + 1 < NST) SCAN_ZISSUE(n + 1);
;                 if (n + 3 < NST) SCAN_ISSUE(n + 3, slot);
.Lld_zwd:
	s_and_b32 s20, s10, 1
	v_lshl_add_u32 v25, s20, 13, v27
	s_cmp_eq_u32 s20, 0
	s_cselect_b32 s20, s44, 0x20200
	v_add_u32_e32 v32, s20, v26
	ds_read_b128 v[28:31], v25 offset:16
	ds_read_b128 v[36:39], v32 offset:16
	ds_read_b128 v[40:43], v25
	ds_read_b128 v[44:47], v32
	s_waitcnt lgkmcnt(0)
.Lld_issue:
	s_mov_b32 s39, m0
	s_cmpk_gt_u32 s45, 0x7e
	s_cbranch_scc1 .Lld_noz
	s_and_b32 s20, s43, 0x2000
	s_add_i32 s20, s41, s20
	v_lshl_add_u64 v[100:101], v[22:23], 0, s[4:5]
	s_mov_b32 m0, s20
	s_addk_i32 s20, 0x400
	global_load_lds_dwordx4 v[22:23], off
	s_mov_b32 m0, s20
	s_nop 0
	global_load_lds_dwordx4 v[100:101], off
.Lld_noz:
	s_cmpk_gt_u32 s45, 0x7c
	s_cbranch_scc1 .Lld_noops
	s_mul_i32 s20, s2, 0x7800
	s_add_i32 s38, s42, s20
	v_lshl_add_u64 v[100:101], v[18:19], 0, s[12:13]
	s_mov_b32 m0, s38
	s_nop 0
	global_load_lds_dwordx4 v[100:101], off nt
	v_lshl_add_u64 v[102:103], v[18:19], 0, s[14:15]
	s_add_i32 s20, s38, 0x400
	s_mov_b32 m0, s20
	s_nop 0
	global_load_lds_dwordx4 v[102:103], off nt
	v_lshl_add_u64 v[100:101], v[18:19], 0, s[16:17]
	s_add_i32 s20, s38, 0x800
	s_mov_b32 m0, s20
	s_nop 0
	global_load_lds_dwordx4 v[100:101], off nt
	v_lshl_add_u64 v[102:103], v[18:19], 0, s[18:19]
	s_add_i32 s20, s38, 0xc00
	s_mov_b32 m0, s20
	s_nop 0
	global_load_lds_dwordx4 v[102:103], off nt
	v_lshl_add_u64 v[100:101], v[18:19], 0, s[24:25]
	s_add_i32 s20, s38, 0x1000
	s_mov_b32 m0, s20
	s_nop 0
	global_load_lds_dwordx4 v[100:101], off nt
	v_lshl_add_u64 v[102:103], v[18:19], 0, s[26:27]
	s_add_i32 s20, s38, 0x1400
	s_mov_b32 m0, s20
	s_nop 0
	global_load_lds_dwordx4 v[102:103], off nt
	v_lshl_add_u64 v[100:101], v[18:19], 0, s[28:29]
	s_add_i32 s20, s38, 0x1800
	s_mov_b32 m0, s20
	s_nop 0
	global_load_lds_dwordx4 v[100:101], off nt
	s_and_b64 vcc, exec, s[8:9]
	s_cbranch_vccnz .Lld_noops
	v_lshl_add_u64 v[102:103], v[18:19], 0, s[30:31]
	s_add_i32 s20, s38, 0x1c00
	s_mov_b32 m0, s20
	s_nop 0
	global_load_lds_dwordx4 v[102:103], off nt
; #define LAS __attribute__((address_space(3)))
; __device__ __forceinline__ unsigned pk2(float lo, float hi) { return pg8::cvt_pk_bf16_v(lo, hi); }
; __device__ __forceinline__ float siluf(float x) { return x * __builtin_amdgcn_rcpf(1.0f + __expf(-x)); }
; __device__ __forceinline__ void unpack8(v4u w, float (&f)[8]) { f[0] = bflo(w.x); f[1] = bfhi(w.x); f[2] = bflo(w.y); f[3] = bfhi(w.y); f[4] = bflo(w.z); f[5] = bfhi(w.z); f[6] = bflo(w.w); f[7] = bfhi(w.w); }
; __device__ __forceinline__ void scan_prompt_wg(const Params& P, LAS unsigned char* lds, int s, int h, int wave, int lane) {
;     ...
;                 float o[16], zf[16]; { float t0[8], t1[8]; unpack8(*(const LAS v4u*)ot, t0); unpack8(*(const LAS v4u*)(ot + 16), t1);
; #pragma unroll
;                     for (int i = 0; i < 8; ++i) { o[i] = t0[i]; o[8 + i] = t1[i]; }
;                     unpack8(*(const LAS v4u*)zt, t0); unpack8(*(const LAS v4u*)(zt + 16), t1);
; #pragma unroll
;                     for (int i = 0; i < 8; ++i) { zf[i] = t0[i]; zf[8 + i] = t1[i]; } }
;                 float ss = 0.f;
; #pragma unroll
;                 for (int i = 0; i < 16; ++i) ss += o[i] * o[i];
;                 ss += __shfl_xor(ss, 1); ss += __shfl_xor(ss, 2);
;                 const float rstd = __builtin_amdgcn_rsqf(ss * (1.0f / 64.0f) + 1e-6f);
;                 float r[16];
; #pragma unroll
;                 for (int i = 0; i < 16; ++i) r[i] = o[i] * rstd * gg[i] * siluf(zf[i]);
;                 bf16* mp = Mr + (size_t)(n - 1) * 64 * 1024;
;                 v4u w0, w1; w0.x = pk2(r[0], r[1]); w0.y = pk2(r[2], r[3]); w0.z = pk2(r[4], r[5]); w0.w = pk2(r[6], r[7]); w1.x = pk2(r[8], r[9]); w1.y = pk2(r[10], r[11]); w1.z = pk2(r[12], r[13]); w1.w = pk2(r[14], r[15]);
;                 *(v4u*)mp = w0; *(v4u*)(mp + 8) = w1;
;             }
;             if (n < NST) {
;                 asm volatile("s_waitcnt lgkmcnt(0)" ::: "memory");
;                 if (n + 1 < NST) SCAN_ZISSUE(n + 1);
;                 if (n + 3 < NST) SCAN_ISSUE(n + 3, slot);
;                 if (n >= 2 && n + 3 < NST) { if (lw < 2) asm volatile("s_waitcnt vmcnt(20)" ::: "memory"); else asm volatile("s_waitcnt vmcnt(18)" ::: "memory"); }
;                 else asm volatile("s_waitcnt vmcnt(0)" ::: "memory");
.Lld_noops:
	s_mov_b32 m0, s39
	s_cmp_eq_u32 s45, 0
	s_cbranch_scc1 .Lld_wait
	v_lshlrev_b32_e32 v34, 16, v31
	v_mul_f32_e32 v33, 0xbfb8aa3b, v34
	v_exp_f32_e32 v48, v33
	v_lshlrev_b32_e32 v62, 16, v29
	s_waitcnt lgkmcnt(2)
	v_lshlrev_b32_e32 v49, 16, v38
	v_add_f32_e32 v25, 1.0, v48
	v_rcp_f32_e32 v25, v25
	v_and_b32_e32 v48, 0xffff0000, v38
	v_and_b32_e32 v63, 0xffff0000, v29
	v_mul_f32_e32 v29, 0xbfb8aa3b, v63
	v_mul_f32_e32 v38, v25, v34
	v_mul_f32_e32 v25, 0xbfb8aa3b, v62
	v_exp_f32_e32 v25, v25
	v_exp_f32_e32 v29, v29
	v_lshlrev_b32_e32 v68, 16, v37
	v_and_b32_e32 v69, 0xffff0000, v37
	v_add_f32_e32 v25, 1.0, v25
	v_rcp_f32_e32 v66, v25
	v_add_f32_e32 v25, 1.0, v29
	v_rcp_f32_e32 v67, v25
	v_and_b32_e32 v37, 0xffff0000, v28
	v_and_b32_e32 v60, 0xffff0000, v31
	s_waitcnt lgkmcnt(1)
	v_lshlrev_b32_e32 v74, 16, v43
	v_pk_mul_f32 v[62:63], v[66:67], v[62:63]
	v_lshlrev_b32_e32 v66, 16, v36
	v_and_b32_e32 v67, 0xffff0000, v36
	v_lshlrev_b32_e32 v36, 16, v28
	v_mul_f32_e32 v25, 0xbfb8aa3b, v36
	v_exp_f32_e32 v25, v25
	v_mul_f32_e32 v28, 0xbfb8aa3b, v37
	v_exp_f32_e32 v31, v28
	v_and_b32_e32 v75, 0xffff0000, v43
	v_add_f32_e32 v25, 1.0, v25
	v_rcp_f32_e32 v72, v25
	v_add_f32_e32 v25, 1.0, v31
	v_rcp_f32_e32 v73, v25
	v_mul_f32_e32 v25, 0xbfb8aa3b, v74
	v_exp_f32_e32 v25, v25
	v_mul_f32_e32 v31, 0xbfb8aa3b, v75
	v_exp_f32_e32 v31, v31
	v_pk_mul_f32 v[36:37], v[72:73], v[36:37]
	v_add_f32_e32 v25, 1.0, v25
	v_rcp_f32_e32 v72, v25
	v_add_f32_e32 v25, 1.0, v31
	v_rcp_f32_e32 v73, v25
	s_waitcnt lgkmcnt(0)
	v_lshlrev_b32_e32 v76, 16, v47
	v_and_b32_e32 v77, 0xffff0000, v47
	v_and_b32_e32 v47, 0xffff0000, v42
	v_pk_mul_f32 v[72:73], v[72:73], v[74:75]
	v_lshlrev_b32_e32 v74, 16, v46
	v_and_b32_e32 v75, 0xffff0000, v46
	v_lshlrev_b32_e32 v46, 16, v42
	v_mul_f32_e32 v25, 0xbfb8aa3b, v46
	v_exp_f32_e32 v25, v25
	v_mul_f32_e32 v31, 0xbfb8aa3b, v47
	v_exp_f32_e32 v31, v31
	v_lshlrev_b32_e32 v84, 16, v41
	v_add_f32_e32 v25, 1.0, v25
	v_rcp_f32_e32 v80, v25
	v_add_f32_e32 v25, 1.0, v31
	v_rcp_f32_e32 v81, v25
	v_and_b32_e32 v85, 0xffff0000, v41
	v_mul_f32_e32 v25, 0xbfb8aa3b, v84
	v_exp_f32_e32 v25, v25
	v_mul_f32_e32 v31, 0xbfb8aa3b, v85
	v_exp_f32_e32 v31, v31
	v_lshlrev_b32_e32 v90, 16, v44
	v_add_f32_e32 v25, 1.0, v25
	v_and_b32_e32 v91, 0xffff0000, v44
	v_lshlrev_b32_e32 v82, 16, v45
	v_and_b32_e32 v83, 0xffff0000, v45
	v_rcp_f32_e32 v88, v25
	v_add_f32_e32 v25, 1.0, v31
	v_lshlrev_b32_e32 v44, 16, v40
	v_and_b32_e32 v45, 0xffff0000, v40
	v_pk_mul_f32 v[40:41], v[90:91], v[90:91]
	v_pk_mul_f32 v[86:87], v[82:83], v[82:83]
	v_rcp_f32_e32 v89, v25
	v_add_f32_e32 v25, v40, v41
	v_add_f32_e32 v25, v86, v25
	v_pk_mul_f32 v[42:43], v[74:75], v[74:75]
	v_add_f32_e32 v25, v87, v25
	v_add_f32_e32 v25, v42, v25
	v_pk_mul_f32 v[78:79], v[76:77], v[76:77]
	v_add_f32_e32 v25, v43, v25
	v_add_f32_e32 v25, v78, v25
	v_pk_mul_f32 v[28:29], v[66:67], v[66:67]
	v_add_f32_e32 v25, v79, v25
	v_add_f32_e32 v25, v28, v25
	v_pk_mul_f32 v[70:71], v[68:69], v[68:69]
	v_add_f32_e32 v25, v29, v25
	v_add_f32_e32 v25, v70, v25
	v_pk_mul_f32 v[50:51], v[48:49], v[48:49]
	v_and_b32_e32 v61, 0xffff0000, v39
	v_add_f32_e32 v25, v71, v25
	v_lshlrev_b32_e32 v33, 16, v39
	v_mov_b32_e32 v32, v61
	v_add_f32_e32 v25, v51, v25
	v_pk_mul_f32 v[64:65], v[32:33], v[32:33]
	v_add_f32_e32 v25, v50, v25
	v_add_f32_e32 v25, v65, v25
	v_add_f32_e32 v25, v64, v25
	ds_bpermute_b32 v28, v57, v25
	v_lshlrev_b32_e32 v50, 16, v30
	v_and_b32_e32 v51, 0xffff0000, v30
	v_mul_f32_e32 v29, 0xbfb8aa3b, v44
	v_mul_f32_e32 v31, 0xbfb8aa3b, v45
	s_waitcnt lgkmcnt(0)
	v_add_f32_e32 v25, v25, v28
	ds_bpermute_b32 v32, v58, v25
	v_mul_f32_e32 v30, 0xbfb8aa3b, v51
	v_exp_f32_e32 v29, v29
	v_exp_f32_e32 v31, v31
	v_exp_f32_e32 v34, v30
	s_waitcnt lgkmcnt(0)
	v_add_f32_e32 v25, v25, v32
	v_fmamk_f32 v25, v25, 0x3c800000, v24
	v_rsq_f32_e32 v32, v25
	v_mul_f32_e32 v25, 0xbfb8aa3b, v50
	v_exp_f32_e32 v25, v25
	v_pk_mul_f32 v[40:41], v[80:81], v[46:47]
	v_pk_mul_f32 v[46:47], v[32:33], v[66:67] op_sel_hi:[0,1]
	v_pk_mul_f32 v[46:47], v[10:11], v[46:47]
	v_add_f32_e32 v25, 1.0, v25
	v_pk_mul_f32 v[36:37], v[36:37], v[46:47]
	v_pk_mul_f32 v[46:47], v[32:33], v[68:69] op_sel_hi:[0,1]
	v_add_f32_e32 v28, 1.0, v29
	v_add_f32_e32 v29, 1.0, v31
	v_pk_mul_f32 v[30:31], v[12:13], v[46:47]
	v_rcp_f32_e32 v46, v25
	v_add_f32_e32 v25, 1.0, v34
	v_rcp_f32_e32 v28, v28
	v_rcp_f32_e32 v29, v29
	v_rcp_f32_e32 v47, v25
	v_mul_f32_e32 v25, 0xbfb8aa3b, v60
	v_exp_f32_e32 v25, v25
	v_pk_mul_f32 v[28:29], v[28:29], v[44:45]
	v_pk_mul_f32 v[44:45], v[32:33], v[90:91] op_sel_hi:[0,1]
	v_pk_mul_f32 v[44:45], v[2:3], v[44:45]
	v_add_f32_e32 v25, 1.0, v25
	v_pk_mul_f32 v[28:29], v[28:29], v[44:45]
	v_pk_mul_f32 v[44:45], v[32:33], v[82:83] op_sel_hi:[0,1]
	v_pk_mul_f32 v[62:63], v[62:63], v[30:31]
	v_pk_mul_f32 v[30:31], v[46:47], v[50:51]
	v_pk_mul_f32 v[46:47], v[32:33], v[48:49] op_sel_hi:[0,1]
	v_rcp_f32_e32 v48, v25
	v_pk_mul_f32 v[42:43], v[88:89], v[84:85]
	v_pk_mul_f32 v[44:45], v[4:5], v[44:45]
	v_pk_mul_f32 v[46:47], v[20:21], v[46:47]
	v_pk_mul_f32 v[42:43], v[42:43], v[44:45]
	v_pk_mul_f32 v[44:45], v[32:33], v[74:75] op_sel_hi:[0,1]
	v_pk_mul_f32 v[44:45], v[6:7], v[44:45]
	v_mov_b32_e32 v49, v32
	v_pk_mul_f32 v[40:41], v[40:41], v[44:45]
	v_pk_mul_f32 v[44:45], v[32:33], v[76:77] op_sel_hi:[0,1]
	v_pk_mul_f32 v[46:47], v[30:31], v[46:47] op_sel:[0,1] op_sel_hi:[1,0]
	v_mul_f32_e32 v30, v32, v33
	v_pk_mul_f32 v[32:33], v[48:49], v[60:61]
	v_pk_mul_f32 v[44:45], v[8:9], v[44:45]
	v_mov_b32_e32 v31, v33
	s_lshl_b64 s[20:21], s[10:11], 17
	v_pk_mul_f32 v[44:45], v[72:73], v[44:45]
	v_pk_mul_f32 v[30:31], v[16:17], v[30:31]
	v_mov_b32_e32 v39, v32
	v_pk_mul_f32 v[32:33], v[38:39], v[30:31]
	v_lshl_add_u64 v[48:49], v[14:15], 0, s[20:21]
	v_readlane_b32 s96, v247, 24
	v_cvt_pk_bf16_f32 v28, v28, v29
	v_cvt_pk_bf16_f32 v29, v42, v43
	v_cvt_pk_bf16_f32 v30, v40, v41
	v_cvt_pk_bf16_f32 v31, v44, v45
	v_cvt_pk_bf16_f32 v36, v36, v37
	v_cvt_pk_bf16_f32 v37, v62, v63
	v_cvt_pk_bf16_f32 v38, v46, v47
	v_cvt_pk_bf16_f32 v39, v32, v33
	global_store_dwordx4 v[48:49], v[28:31], off
	global_store_dwordx4 v[48:49], v[36:39], off offset:16
.Lld_wait:
	s_cmpk_eq_i32 s45, 0x80
	s_cbranch_scc1 .Lld_exit
	s_cmpk_gt_u32 s45, 0x7c
	s_cbranch_scc1 .Lld_w0
	s_and_b64 vcc, exec, s[8:9]
	s_cmp_lt_u32 s45, 2
	s_cbranch_scc1 .Lld_wearly
	s_cbranch_vccnz .Lld_w22
	s_waitcnt vmcnt(24)
	s_branch .Lld_bar
.Lld_w22:
	s_waitcnt vmcnt(22)
	s_branch .Lld_bar
.Lld_wearly:
	s_cbranch_vccnz .Lld_w16
	s_waitcnt vmcnt(18)
	s_branch .Lld_bar
.Lld_w16:
	s_waitcnt vmcnt(16)
	s_branch .Lld_bar

; #define SCAN_BAR() do { asm volatile("" ::: "memory"); __builtin_amdgcn_s_barrier(); asm volatile("" ::: "memory"); } while (0)
; #define SCAN_ISSUE(n, slot) do { const unsigned char* s_ = src + (size_t)(n) * step_stride; LAS unsigned char* d_ = lds + (slot) * SR_SLOT + p0 * 1024; \
;         _Pragma("unroll") for (int i_ = 0; i_ < 7; ++i_) glds16_asm(s_ + i_ * 1024, d_ + i_ * 1024, true  ); \
;         if (lw < 2) glds16_asm(s_ + 7 * 1024, d_ + 7 * 1024, true); } while (0)
; #define SCAN_ZISSUE(n) do { const unsigned char* z_ = zsrc + (size_t)(n) * 64 * 2048; LAS unsigned char* d_ = lds + ZT_OFF + ((n) & 1) * 8192 + (2 * lw) * 1024; \
;         glds16_asm(z_, d_, false); glds16_asm(z_ + 8 * 2048, d_ + 1024, false); } while (0)
; __device__ __forceinline__ void scan_prompt_wg(const Params& P, LAS unsigned char* lds, int s, int h, int wave, int lane) {
;     ...
;                 if (n + 1 < NST) SCAN_ZISSUE(n + 1);
;                 if (n + 3 < NST) SCAN_ISSUE(n + 3, slot);
;                 if (n >= 2 && n + 3 < NST) { if (lw < 2) asm volatile("s_waitcnt vmcnt(20)" ::: "memory"); else asm volatile("s_waitcnt vmcnt(18)" ::: "memory"); }
;                 else asm volatile("s_waitcnt vmcnt(0)" ::: "memory");
;                 slot = (slot == SR_NS - 1) ? 0 : slot + 1;
;                 SCAN_BAR();
;             }
.Lld_bar:
	s_add_i32 s10, s2, 1
	s_barrier
	s_cmp_lg_u32 s2, 3
	s_cselect_b32 s2, s10, 0
	s_addk_i32 s43, 0x2000
	v_lshl_add_u64 v[18:19], v[18:19], 0, s[34:35]
	v_lshl_add_u64 v[22:23], v[22:23], 0, s[36:37]
	s_mov_b32 s10, s45
	s_branch .LBB0_666
.Lld_exit:
	v_readlane_b32 s96, v247, 24
	s_nop 3
